# hand-written lean epilogue for the past-K up-projection GEMM (saddr stores, permlane swaps instead of bpermute) on top of G2 loop rewrite
# speedup vs baseline: 1.0062x; 1.0062x over previous
.LBB0_345:
	s_lshl_b32 s53, s24, 20
	s_lshl_b32 s56, s22, 17
	s_add_u32 s53, s53, s56
	s_add_u32 s54, s14, s53
	s_addc_u32 s55, s15, 0
	s_lshr_b32 s56, s24, 4
	s_lshl_b32 s56, s56, 4
	s_lshl_b32 s57, s22, 1
	s_add_i32 s56, s56, s57
	s_lshl_b32 s56, s56, 12
	s_and_b32 s57, s24, 15
	s_lshl_b32 s57, s57, 8
	s_add_i32 s56, s56, s57
	s_lshl_b32 s56, s56, 2
	s_add_u32 s58, s16, s56
	s_addc_u32 s59, s17, 0
	v_and_b32_e32 v145, 0xff, v0
	v_and_b32_e32 v146, 0x100, v0
	v_lshlrev_b32_e32 v145, 4, v145
	v_lshl_or_b32 v144, v146, 7, v145
	v_add_u32_e32 v172, 0x800, v144
	v_add_u32_e32 v173, 0x2000, v172
	v_add_u32_e32 v174, 0x4000, v172
	v_add_u32_e32 v175, 0x6000, v172
	v_add_u32_e32 v176, 0x10000, v172
	v_add_u32_e32 v177, 0x12000, v172
	v_add_u32_e32 v178, 0x14000, v172
	v_add_u32_e32 v179, 0x16000, v172
	v_and_b32_e32 v147, 0xc0, v0
	v_and_b32_e32 v149, 63, v0
	v_lshlrev_b32_e32 v147, 17, v147
	v_lshlrev_b32_e32 v149, 2, v149
	v_or3_b32 v147, v147, v146, v149
	v_add_u32_e32 v148, 0x4000, v147
	v_cvt_pk_bf16_f32 v152, v128, v129
	v_cvt_pk_bf16_f32 v153, v130, v131
	v_cvt_pk_bf16_f32 v154, v124, v125
	v_cvt_pk_bf16_f32 v155, v126, v127
	global_store_dwordx4 v172, v[152:155], s[54:55] offset:-2048
	v_cvt_pk_bf16_f32 v156, v120, v121
	v_cvt_pk_bf16_f32 v157, v122, v123
	v_cvt_pk_bf16_f32 v158, v112, v113
	v_cvt_pk_bf16_f32 v159, v114, v115
	global_store_dwordx4 v172, v[156:159], s[54:55] offset:2048
	v_cvt_pk_bf16_f32 v160, v116, v117
	v_cvt_pk_bf16_f32 v161, v118, v119
	v_cvt_pk_bf16_f32 v162, v108, v109
	v_cvt_pk_bf16_f32 v163, v110, v111
	global_store_dwordx4 v173, v[160:163], s[54:55] offset:-2048
	v_cvt_pk_bf16_f32 v168, v104, v105
	v_cvt_pk_bf16_f32 v169, v106, v107
	v_cvt_pk_bf16_f32 v170, v96, v97
	v_cvt_pk_bf16_f32 v171, v98, v99
	global_store_dwordx4 v173, v[168:171], s[54:55] offset:2048
	v_cvt_pk_bf16_f32 v152, v100, v101
	v_cvt_pk_bf16_f32 v153, v102, v103
	v_cvt_pk_bf16_f32 v154, v92, v93
	v_cvt_pk_bf16_f32 v155, v94, v95
	global_store_dwordx4 v174, v[152:155], s[54:55] offset:-2048
	v_cvt_pk_bf16_f32 v156, v88, v89
	v_cvt_pk_bf16_f32 v157, v90, v91
	v_cvt_pk_bf16_f32 v158, v80, v81
	v_cvt_pk_bf16_f32 v159, v82, v83
	global_store_dwordx4 v174, v[156:159], s[54:55] offset:2048
	v_cvt_pk_bf16_f32 v160, v84, v85
	v_cvt_pk_bf16_f32 v161, v86, v87
	v_cvt_pk_bf16_f32 v162, v76, v77
	v_cvt_pk_bf16_f32 v163, v78, v79
	global_store_dwordx4 v175, v[160:163], s[54:55] offset:-2048
	v_cvt_pk_bf16_f32 v168, v72, v73
	v_cvt_pk_bf16_f32 v169, v74, v75
	v_cvt_pk_bf16_f32 v170, v68, v69
	v_cvt_pk_bf16_f32 v171, v70, v71
	global_store_dwordx4 v175, v[168:171], s[54:55] offset:2048
	v_cvt_pk_bf16_f32 v152, v64, v65
	v_cvt_pk_bf16_f32 v153, v66, v67
	v_cvt_pk_bf16_f32 v154, v60, v61
	v_cvt_pk_bf16_f32 v155, v62, v63
	global_store_dwordx4 v176, v[152:155], s[54:55] offset:-2048
	v_cvt_pk_bf16_f32 v156, v56, v57
	v_cvt_pk_bf16_f32 v157, v58, v59
	v_cvt_pk_bf16_f32 v158, v48, v49
	v_cvt_pk_bf16_f32 v159, v50, v51
	global_store_dwordx4 v176, v[156:159], s[54:55] offset:2048
	v_cvt_pk_bf16_f32 v160, v52, v53
	v_cvt_pk_bf16_f32 v161, v54, v55
	v_cvt_pk_bf16_f32 v162, v44, v45
	v_cvt_pk_bf16_f32 v163, v46, v47
	global_store_dwordx4 v177, v[160:163], s[54:55] offset:-2048
	v_cvt_pk_bf16_f32 v168, v40, v41
	v_cvt_pk_bf16_f32 v169, v42, v43
	v_cvt_pk_bf16_f32 v170, v32, v33
	v_cvt_pk_bf16_f32 v171, v34, v35
	global_store_dwordx4 v177, v[168:171], s[54:55] offset:2048
	v_cvt_pk_bf16_f32 v152, v36, v37
	v_cvt_pk_bf16_f32 v153, v38, v39
	v_cvt_pk_bf16_f32 v154, v28, v29
	v_cvt_pk_bf16_f32 v155, v30, v31
	global_store_dwordx4 v178, v[152:155], s[54:55] offset:-2048
	v_cvt_pk_bf16_f32 v156, v24, v25
	v_cvt_pk_bf16_f32 v157, v26, v27
	v_cvt_pk_bf16_f32 v158, v16, v17
	v_cvt_pk_bf16_f32 v159, v18, v19
	global_store_dwordx4 v178, v[156:159], s[54:55] offset:2048
	v_cvt_pk_bf16_f32 v160, v20, v21
	v_cvt_pk_bf16_f32 v161, v22, v23
	v_cvt_pk_bf16_f32 v162, v12, v13
	v_cvt_pk_bf16_f32 v163, v14, v15
	global_store_dwordx4 v179, v[160:163], s[54:55] offset:-2048
	v_cvt_pk_bf16_f32 v168, v8, v9
	v_cvt_pk_bf16_f32 v169, v10, v11
	v_cvt_pk_bf16_f32 v170, v4, v5
	v_cvt_pk_bf16_f32 v171, v6, v7
	global_store_dwordx4 v179, v[168:171], s[54:55] offset:2048
	v_mul_f32_e32 v180, v128, v128
	v_mul_f32_e32 v181, v116, v116
	v_mul_f32_e32 v182, v100, v100
	v_mul_f32_e32 v183, v84, v84
	v_fmac_f32_e32 v180, v129, v129
	v_fmac_f32_e32 v181, v117, v117
	v_fmac_f32_e32 v182, v101, v101
	v_fmac_f32_e32 v183, v85, v85
	v_fmac_f32_e32 v180, v130, v130
	v_fmac_f32_e32 v181, v118, v118
	v_fmac_f32_e32 v182, v102, v102
	v_fmac_f32_e32 v183, v86, v86
	v_fmac_f32_e32 v180, v131, v131
	v_fmac_f32_e32 v181, v119, v119
	v_fmac_f32_e32 v182, v103, v103
	v_fmac_f32_e32 v183, v87, v87
	v_fmac_f32_e32 v180, v124, v124
	v_fmac_f32_e32 v181, v108, v108
	v_fmac_f32_e32 v182, v92, v92
	v_fmac_f32_e32 v183, v76, v76
	v_fmac_f32_e32 v180, v125, v125
	v_fmac_f32_e32 v181, v109, v109
	v_fmac_f32_e32 v182, v93, v93
	v_fmac_f32_e32 v183, v77, v77
	v_fmac_f32_e32 v180, v126, v126
	v_fmac_f32_e32 v181, v110, v110
	v_fmac_f32_e32 v182, v94, v94
	v_fmac_f32_e32 v183, v78, v78
	v_fmac_f32_e32 v180, v127, v127
	v_fmac_f32_e32 v181, v111, v111
	v_fmac_f32_e32 v182, v95, v95
	v_fmac_f32_e32 v183, v79, v79
	v_mul_f32_e32 v184, v120, v120
	v_mul_f32_e32 v185, v104, v104
	v_mul_f32_e32 v186, v88, v88
	v_mul_f32_e32 v187, v72, v72
	v_fmac_f32_e32 v184, v121, v121
	v_fmac_f32_e32 v185, v105, v105
	v_fmac_f32_e32 v186, v89, v89
	v_fmac_f32_e32 v187, v73, v73
	v_fmac_f32_e32 v184, v122, v122
	v_fmac_f32_e32 v185, v106, v106
	v_fmac_f32_e32 v186, v90, v90
	v_fmac_f32_e32 v187, v74, v74
	v_fmac_f32_e32 v184, v123, v123
	v_fmac_f32_e32 v185, v107, v107
	v_fmac_f32_e32 v186, v91, v91
	v_fmac_f32_e32 v187, v75, v75
	v_fmac_f32_e32 v184, v112, v112
	v_fmac_f32_e32 v185, v96, v96
	v_fmac_f32_e32 v186, v80, v80
	v_fmac_f32_e32 v187, v68, v68
	v_fmac_f32_e32 v184, v113, v113
	v_fmac_f32_e32 v185, v97, v97
	v_fmac_f32_e32 v186, v81, v81
	v_fmac_f32_e32 v187, v69, v69
	v_fmac_f32_e32 v184, v114, v114
	v_fmac_f32_e32 v185, v98, v98
	v_fmac_f32_e32 v186, v82, v82
	v_fmac_f32_e32 v187, v70, v70
	v_fmac_f32_e32 v184, v115, v115
	v_fmac_f32_e32 v185, v99, v99
	v_fmac_f32_e32 v186, v83, v83
	v_fmac_f32_e32 v187, v71, v71
	v_mul_f32_e32 v188, v64, v64
	v_mul_f32_e32 v189, v52, v52
	v_mul_f32_e32 v190, v36, v36
	v_mul_f32_e32 v191, v20, v20
	v_fmac_f32_e32 v188, v65, v65
	v_fmac_f32_e32 v189, v53, v53
	v_fmac_f32_e32 v190, v37, v37
	v_fmac_f32_e32 v191, v21, v21
	v_fmac_f32_e32 v188, v66, v66
	v_fmac_f32_e32 v189, v54, v54
	v_fmac_f32_e32 v190, v38, v38
	v_fmac_f32_e32 v191, v22, v22
	v_fmac_f32_e32 v188, v67, v67
	v_fmac_f32_e32 v189, v55, v55
	v_fmac_f32_e32 v190, v39, v39
	v_fmac_f32_e32 v191, v23, v23
	v_fmac_f32_e32 v188, v60, v60
	v_fmac_f32_e32 v189, v44, v44
	v_fmac_f32_e32 v190, v28, v28
	v_fmac_f32_e32 v191, v12, v12
	v_fmac_f32_e32 v188, v61, v61
	v_fmac_f32_e32 v189, v45, v45
	v_fmac_f32_e32 v190, v29, v29
	v_fmac_f32_e32 v191, v13, v13
	v_fmac_f32_e32 v188, v62, v62
	v_fmac_f32_e32 v189, v46, v46
	v_fmac_f32_e32 v190, v30, v30
	v_fmac_f32_e32 v191, v14, v14
	v_fmac_f32_e32 v188, v63, v63
	v_fmac_f32_e32 v189, v47, v47
	v_fmac_f32_e32 v190, v31, v31
	v_fmac_f32_e32 v191, v15, v15
	v_mul_f32_e32 v192, v56, v56
	v_mul_f32_e32 v193, v40, v40
	v_mul_f32_e32 v194, v24, v24
	v_mul_f32_e32 v195, v8, v8
	v_fmac_f32_e32 v192, v57, v57
	v_fmac_f32_e32 v193, v41, v41
	v_fmac_f32_e32 v194, v25, v25
	v_fmac_f32_e32 v195, v9, v9
	v_fmac_f32_e32 v192, v58, v58
	v_fmac_f32_e32 v193, v42, v42
	v_fmac_f32_e32 v194, v26, v26
	v_fmac_f32_e32 v195, v10, v10
	v_fmac_f32_e32 v192, v59, v59
	v_fmac_f32_e32 v193, v43, v43
	v_fmac_f32_e32 v194, v27, v27
	v_fmac_f32_e32 v195, v11, v11
	v_fmac_f32_e32 v192, v48, v48
	v_fmac_f32_e32 v193, v32, v32
	v_fmac_f32_e32 v194, v16, v16
	v_fmac_f32_e32 v195, v4, v4
	v_fmac_f32_e32 v192, v49, v49
	v_fmac_f32_e32 v193, v33, v33
	v_fmac_f32_e32 v194, v17, v17
	v_fmac_f32_e32 v195, v5, v5
	v_fmac_f32_e32 v192, v50, v50
	v_fmac_f32_e32 v193, v34, v34
	v_fmac_f32_e32 v194, v18, v18
	v_fmac_f32_e32 v195, v6, v6
	v_fmac_f32_e32 v192, v51, v51
	v_fmac_f32_e32 v193, v35, v35
	v_fmac_f32_e32 v194, v19, v19
	v_fmac_f32_e32 v195, v7, v7
	v_permlane32_swap_b32_e32 v180, v182
	v_permlane32_swap_b32_e32 v181, v183
	v_permlane32_swap_b32_e32 v184, v186
	v_permlane32_swap_b32_e32 v185, v187
	v_permlane32_swap_b32_e32 v188, v190
	v_permlane32_swap_b32_e32 v189, v191
	v_permlane32_swap_b32_e32 v192, v194
	v_permlane32_swap_b32_e32 v193, v195
	v_add_f32_e32 v180, v180, v182
	v_add_f32_e32 v181, v181, v183
	v_add_f32_e32 v184, v184, v186
	v_add_f32_e32 v185, v185, v187
	v_add_f32_e32 v188, v188, v190
	v_add_f32_e32 v189, v189, v191
	v_add_f32_e32 v192, v192, v194
	v_add_f32_e32 v193, v193, v195
	s_nop 1
	v_permlane16_swap_b32_e32 v180, v181
	v_permlane16_swap_b32_e32 v184, v185
	v_permlane16_swap_b32_e32 v188, v189
	v_permlane16_swap_b32_e32 v192, v193
	v_add_f32_e32 v180, v180, v181
	v_add_f32_e32 v184, v184, v185
	v_add_f32_e32 v188, v188, v189
	v_add_f32_e32 v192, v192, v193
	global_store_dword v147, v180, s[58:59]
	global_store_dword v148, v184, s[58:59]
	global_store_dword v147, v188, s[58:59] offset:512
	global_store_dword v148, v192, s[58:59] offset:512
	s_andn2_b64 vcc, exec, s[42:43]
	s_mov_b64 s[22:23], -1
	s_cbranch_vccnz .LBB0_334
	s_andn2_b64 vcc, exec, s[12:13]
	s_cbranch_vccnz .LBB0_333
	s_barrier
	s_branch .LBB0_333
